# instruction selection: phase-0 f32-to-bf16 row copies pack with v_cvt_pk_bf16_f32 (2 ops per 4 values) instead of the 12-op bit-trick RNE, on top of v86
# baseline (speedup 1.0000x reference)
.LBB0_3254:
	global_load_dwordx4 v[140:143], v0, s[10:11]
	global_load_dwordx4 v[144:147], v0, s[10:11] offset:1024
	global_load_dwordx4 v[148:151], v0, s[10:11] offset:2048
	global_load_dwordx4 v[152:155], v0, s[10:11] offset:3072
	v_lshl_add_u64 v[8:9], s[10:11], 0, v[0:1]
	v_add_co_u32_e32 v8, vcc, s73, v8
	s_nop 1
	v_addc_co_u32_e32 v9, vcc, 0, v9, vcc
	global_load_dwordx4 v[156:159], v[8:9], off
	global_load_dwordx4 v[160:163], v[8:9], off offset:1024
	global_load_dwordx4 v[164:167], v[8:9], off offset:2048
	global_load_dwordx4 v[168:171], v[8:9], off offset:3072
	s_lshl_b64 s[0:1], s[8:9], 12
	s_add_u32 s8, s92, s0
	s_addc_u32 s9, s93, s1
	s_add_u32 s6, s6, s50
	s_addc_u32 s7, s7, s51
	s_add_u32 s2, s2, s74
	s_addc_u32 s3, s3, s75
	s_cmpk_gt_i32 s6, 0x21ff
	s_waitcnt vmcnt(7)
	v_cvt_pk_bf16_f32 v140, v140, v141
	v_cvt_pk_bf16_f32 v141, v142, v143
	global_store_dwordx2 v2, v[140:141], s[8:9]
	s_waitcnt vmcnt(7)
	v_cvt_pk_bf16_f32 v144, v144, v145
	v_cvt_pk_bf16_f32 v145, v146, v147
	global_store_dwordx2 v2, v[144:145], s[8:9] offset:512
	s_waitcnt vmcnt(7)
	v_cvt_pk_bf16_f32 v148, v148, v149
	v_cvt_pk_bf16_f32 v149, v150, v151
	global_store_dwordx2 v2, v[148:149], s[8:9] offset:1024
	s_waitcnt vmcnt(7)
	v_cvt_pk_bf16_f32 v152, v152, v153
	v_cvt_pk_bf16_f32 v153, v154, v155
	global_store_dwordx2 v2, v[152:153], s[8:9] offset:1536
	s_waitcnt vmcnt(7)
	v_cvt_pk_bf16_f32 v156, v156, v157
	v_cvt_pk_bf16_f32 v157, v158, v159
	global_store_dwordx2 v2, v[156:157], s[8:9] offset:2048
	s_waitcnt vmcnt(7)
	v_cvt_pk_bf16_f32 v160, v160, v161
	v_cvt_pk_bf16_f32 v161, v162, v163
	global_store_dwordx2 v2, v[160:161], s[8:9] offset:2560
	s_waitcnt vmcnt(7)
	v_cvt_pk_bf16_f32 v164, v164, v165
	v_cvt_pk_bf16_f32 v165, v166, v167
	global_store_dwordx2 v2, v[164:165], s[8:9] offset:3072
	s_waitcnt vmcnt(7)
	v_cvt_pk_bf16_f32 v168, v168, v169
	v_cvt_pk_bf16_f32 v169, v170, v171
	global_store_dwordx2 v2, v[168:169], s[8:9] offset:3584
	s_cbranch_scc1 .LBB0_3259

.LBB0_3261:
	s_mov_b32 s0, 1
	s_ashr_i32 s1, s0, 31
	s_lshl_b64 s[0:1], s[0:1], 3
	s_add_u32 s0, s48, s0
	s_addc_u32 s1, s49, s1
	s_load_dwordx2 s[0:1], s[0:1], 0x0
	s_add_i32 s18, s18, s50
	s_waitcnt lgkmcnt(0)
	v_lshl_add_u64 v[8:9], s[0:1], 0, v[2:3]
	global_load_dwordx4 v[140:143], v[8:9], off offset:-4096
	global_load_dwordx4 v[144:147], v[8:9], off offset:-3072
	global_load_dwordx4 v[148:151], v[8:9], off offset:-2048
	global_load_dwordx4 v[152:155], v[8:9], off offset:-1024
	global_load_dwordx4 v[156:159], v[8:9], off offset:0
	global_load_dwordx4 v[160:163], v[8:9], off offset:1024
	global_load_dwordx4 v[164:167], v[8:9], off offset:2048
	global_load_dwordx4 v[168:171], v[8:9], off offset:3072
	v_lshl_add_u64 v[2:3], v[2:3], 0, s[74:75]
	s_waitcnt vmcnt(7)
	v_cvt_pk_bf16_f32 v140, v140, v141
	v_cvt_pk_bf16_f32 v141, v142, v143
	global_store_dwordx2 v0, v[140:141], s[2:3]
	s_waitcnt vmcnt(7)
	v_cvt_pk_bf16_f32 v144, v144, v145
	v_cvt_pk_bf16_f32 v145, v146, v147
	global_store_dwordx2 v0, v[144:145], s[2:3] offset:512
	s_waitcnt vmcnt(7)
	v_cvt_pk_bf16_f32 v148, v148, v149
	v_cvt_pk_bf16_f32 v149, v150, v151
	global_store_dwordx2 v0, v[148:149], s[2:3] offset:1024
	s_waitcnt vmcnt(7)
	v_cvt_pk_bf16_f32 v152, v152, v153
	v_cvt_pk_bf16_f32 v153, v154, v155
	global_store_dwordx2 v0, v[152:153], s[2:3] offset:1536
	s_waitcnt vmcnt(7)
	v_cvt_pk_bf16_f32 v156, v156, v157
	v_cvt_pk_bf16_f32 v157, v158, v159
	global_store_dwordx2 v0, v[156:157], s[2:3] offset:2048
	s_waitcnt vmcnt(7)
	v_cvt_pk_bf16_f32 v160, v160, v161
	v_cvt_pk_bf16_f32 v161, v162, v163
	global_store_dwordx2 v0, v[160:161], s[2:3] offset:2560
	s_waitcnt vmcnt(7)
	v_cvt_pk_bf16_f32 v164, v164, v165
	v_cvt_pk_bf16_f32 v165, v166, v167
	global_store_dwordx2 v0, v[164:165], s[2:3] offset:3072
	s_waitcnt vmcnt(7)
	v_cvt_pk_bf16_f32 v168, v168, v169
	v_cvt_pk_bf16_f32 v169, v170, v171
	global_store_dwordx2 v0, v[168:169], s[2:3] offset:3584
	s_add_u32 s2, s2, s70
	s_addc_u32 s3, s3, s71
	s_cmpk_gt_i32 s18, 0x3ff
	s_cbranch_scc0 .LBB0_3261
	s_getpc_b64 s[98:99]
